# P0: W8 forget-gate weight staging with all 16 loads per thread in flight (one round trip instead of four)
# speedup vs baseline: 1.0163x; 1.0023x over previous
.LBB0_13:
	s_load_dwordx16 s[56:71], s[0:1], 0x0
	s_movk_i32 s0, 0x2000
	v_writelane_b32 v254, s21, 22
	v_cmp_gt_i32_e32 vcc, s0, v2
	v_and_b32_e32 v18, 7, v2
	s_and_saveexec_b64 s[2:3], vcc
	s_cbranch_execz .LBB0_25
	v_readlane_b32 s36, v254, 4
	v_readlane_b32 s37, v254, 5
	v_lshrrev_b32_e32 v26, 3, v2
	v_mul_u32_u24_e32 v27, 0x4020, v26
	v_lshl_add_u32 v27, v18, 2, v27
	v_add_u32_e32 v27, 0x1800, v27
	v_lshl_add_u32 v28, v26, 2, 0
	v_lshl_add_u32 v28, v18, 12, v28
	v_add_u32_e32 v28, 0x12000, v28
	global_load_dword v30, v27, s[36:37]
	v_add_u32_e32 v29, 0x100800, v27
	global_load_dword v31, v29, s[36:37]
	v_add_u32_e32 v29, 0x201000, v27
	global_load_dword v32, v29, s[36:37]
	v_add_u32_e32 v29, 0x301800, v27
	global_load_dword v33, v29, s[36:37]
	v_add_u32_e32 v29, 0x402000, v27
	global_load_dword v34, v29, s[36:37]
	v_add_u32_e32 v29, 0x502800, v27
	global_load_dword v35, v29, s[36:37]
	v_add_u32_e32 v29, 0x603000, v27
	global_load_dword v36, v29, s[36:37]
	v_add_u32_e32 v29, 0x703800, v27
	global_load_dword v37, v29, s[36:37]
	v_add_u32_e32 v29, 0x804000, v27
	global_load_dword v38, v29, s[36:37]
	v_add_u32_e32 v29, 0x904800, v27
	global_load_dword v39, v29, s[36:37]
	v_add_u32_e32 v29, 0xa05000, v27
	global_load_dword v40, v29, s[36:37]
	v_add_u32_e32 v29, 0xb05800, v27
	global_load_dword v41, v29, s[36:37]
	v_add_u32_e32 v29, 0xc06000, v27
	global_load_dword v42, v29, s[36:37]
	v_add_u32_e32 v29, 0xd06800, v27
	global_load_dword v43, v29, s[36:37]
	v_add_u32_e32 v29, 0xe07000, v27
	global_load_dword v44, v29, s[36:37]
	v_add_u32_e32 v29, 0xf07800, v27
	global_load_dword v45, v29, s[36:37]
	s_waitcnt vmcnt(15)
	ds_write_b32 v28, v30
	s_waitcnt vmcnt(14)
	ds_write_b32 v28, v31 offset:256
	s_waitcnt vmcnt(13)
	ds_write_b32 v28, v32 offset:512
	s_waitcnt vmcnt(12)
	ds_write_b32 v28, v33 offset:768
	s_waitcnt vmcnt(11)
	ds_write_b32 v28, v34 offset:1024
	s_waitcnt vmcnt(10)
	ds_write_b32 v28, v35 offset:1280
	s_waitcnt vmcnt(9)
	ds_write_b32 v28, v36 offset:1536
	s_waitcnt vmcnt(8)
	ds_write_b32 v28, v37 offset:1792
	s_waitcnt vmcnt(7)
	ds_write_b32 v28, v38 offset:2048
	s_waitcnt vmcnt(6)
	ds_write_b32 v28, v39 offset:2304
	s_waitcnt vmcnt(5)
	ds_write_b32 v28, v40 offset:2560
	s_waitcnt vmcnt(4)
	ds_write_b32 v28, v41 offset:2816
	s_waitcnt vmcnt(3)
	ds_write_b32 v28, v42 offset:3072
	s_waitcnt vmcnt(2)
	ds_write_b32 v28, v43 offset:3328
	s_waitcnt vmcnt(1)
	ds_write_b32 v28, v44 offset:3584
	s_waitcnt vmcnt(0)
	ds_write_b32 v28, v45 offset:3840

.Lpost_getpc1:
	s_add_u32 s98, s98, (.LBB0_930-.Lpost_getpc1)&4294967295
	s_addc_u32 s99, s99, (.LBB0_930-.Lpost_getpc1)>>32
	s_setpc_b64 s[98:99]
	s_nop 0
	s_nop 0
	s_nop 0
	s_nop 0
	s_nop 0
	s_nop 0
	s_nop 0
	s_nop 0
	s_nop 0
	s_nop 0
	s_nop 0
	s_nop 0
	s_nop 0
	s_nop 0
	s_nop 0
	s_nop 0
	s_nop 0
	s_nop 0
	s_nop 0
	s_nop 0
	s_nop 0
	s_nop 0
	s_nop 0
	s_nop 0
	s_nop 0
	s_nop 0
	s_nop 0
	s_nop 0
	s_nop 0
	s_nop 0
	s_nop 0
	s_nop 0
	s_nop 0
	s_nop 0
